# P0 input loads (x, weights) marked non-temporal (nt): read-once streams no longer displace P0's outputs from cache
# speedup vs baseline: 1.0417x; 1.0334x over previous
; #define LAS __attribute__((address_space(3)))
; __device__ __forceinline__ unsigned pk_bf16(float lo, float hi) { typedef __bf16 b2 __attribute__((ext_vector_type(2))); f32x2 v = {lo, hi}; b2 b = __builtin_convertvector(v, b2); return __builtin_bit_cast(unsigned, b); }
; template <bool MAP> __device__ __forceinline__ void p0_transpose_item(const float* W, int K, int N, u16* WT, LAS float* scr, int item, int lane) {
;     const int nblk = N / 32, kb = item / nblk, nb = item % nblk, k0 = 64 * kb, n0 = 32 * nb;
;     float tv[32];
; #pragma unroll
;     for (int i = 0; i < 32; ++i) tv[i] = W[(size_t)(k0 + 2 * i + (lane >> 5)) * N + n0 + (lane & 31)];
; #pragma unroll
;     for (int i = 0; i < 32; ++i) scr[(2 * i + (lane >> 5)) * 33 + (lane & 31)] = tv[i];
;     asm volatile("s_waitcnt lgkmcnt(0)" ::: "memory");
;     const int c = lane & 7;
; #pragma unroll
;     for (int j = 0; j < 4; ++j) { const int n = (lane >> 3) + 8 * j; const LAS float* s = scr + (8 * c) * 33 + n;
;         u32x4 o; o.x = pk_bf16(s[0 * 33], s[1 * 33]); o.y = pk_bf16(s[2 * 33], s[3 * 33]); o.z = pk_bf16(s[4 * 33], s[5 * 33]); o.w = pk_bf16(s[6 * 33], s[7 * 33]);
;         const int r = MAP ? wt_row_of_col(n0 + n) : (n0 + n);
;         *(u32x4*)(WT + (size_t)r * K + k0 + 8 * c) = o; }
;     asm volatile("s_waitcnt lgkmcnt(0)" ::: "memory");
; __device__ __forceinline__ void p0_prologue(const Ptrs& P, LAS unsigned char* lds, int vcu, int G) {
;     ...
;     for (int it = gw; it < NITEMS; it += NGW) {
;         int r = it;
;         if (r < I_IN) { p0_transpose_item<true>(P.w_in, 1024, NIN, (u16*)(P.ws + WS_WT), scr, r, lane); continue; } r -= I_IN;
;         if (r < I_A) { p0_transpose_item<false>(P.wa, 1024, 1024, (u16*)(P.ws + WS_WA), scr, r, lane); continue; } r -= I_A;
;         if (r < I_B) { p0_transpose_item<false>(P.wb, 512, 1024, (u16*)(P.ws + WS_WB), scr, r, lane); continue; } r -= I_B;
;         p0_transpose_item<false>(P.wo, 1024, 1024, (u16*)(P.ws + WS_WO), scr, r, lane);
.LBB0_24:
	s_cmpk_gt_i32 s28, 0x15ff
	s_mov_b64 s[8:9], -1
	s_cbranch_scc0 .LBB0_34
	s_cmpk_gt_u32 s28, 0x17ff
	s_cbranch_scc0 .LBB0_31
	s_cmpk_gt_u32 s28, 0x18ff
	s_cbranch_scc0 .LBB0_28
	s_add_i32 s8, s18, 0xfffce000
	s_and_b32 s8, s8, 0x3e0
	s_and_b32 s9, s21, 0xf0000
	s_or_b32 s9, s9, s8
	v_or_b32_e32 v0, s9, v26
	v_or_b32_e32 v14, s9, v29
	v_or_b32_e32 v15, s9, v30
	v_or_b32_e32 v16, s9, v31
	v_or_b32_e32 v17, s9, v32
	v_or_b32_e32 v18, s9, v33
	v_lshlrev_b32_e32 v0, 2, v0
	v_or_b32_e32 v12, s9, v27
	v_or_b32_e32 v13, s9, v28
	v_lshlrev_b32_e32 v14, 2, v14
	v_lshlrev_b32_e32 v15, 2, v15
	v_lshlrev_b32_e32 v16, 2, v16
	v_lshlrev_b32_e32 v17, 2, v17
	v_lshlrev_b32_e32 v18, 2, v18
	v_lshlrev_b32_e32 v12, 2, v12
	v_lshlrev_b32_e32 v13, 2, v13
	global_load_dword v19, v0, s[72:73] nt
	global_load_dword v20, v12, s[72:73] nt
	global_load_dword v21, v13, s[72:73] nt
	s_nop 0
	global_load_dword v14, v14, s[72:73] nt
	s_nop 0
	global_load_dword v15, v15, s[72:73] nt
	s_nop 0
	global_load_dword v16, v16, s[72:73] nt
	s_nop 0
	global_load_dword v17, v17, s[72:73] nt
	s_nop 0
	global_load_dword v18, v18, s[72:73] nt
	v_or_b32_e32 v0, s9, v34
	v_or_b32_e32 v22, s9, v37
	v_or_b32_e32 v23, s9, v38
	v_or_b32_e32 v71, s9, v39
	v_or_b32_e32 v72, s9, v40
	v_or_b32_e32 v73, s9, v41
	v_lshlrev_b32_e32 v0, 2, v0
	v_or_b32_e32 v12, s9, v35
	v_or_b32_e32 v13, s9, v36
	v_lshlrev_b32_e32 v22, 2, v22
	v_lshlrev_b32_e32 v23, 2, v23
	v_lshlrev_b32_e32 v71, 2, v71
	v_lshlrev_b32_e32 v72, 2, v72
	v_lshlrev_b32_e32 v73, 2, v73
	v_lshlrev_b32_e32 v12, 2, v12
	v_lshlrev_b32_e32 v13, 2, v13
	global_load_dword v74, v0, s[72:73] nt
	global_load_dword v75, v12, s[72:73] nt
	global_load_dword v76, v13, s[72:73] nt
	s_nop 0
	global_load_dword v22, v22, s[72:73] nt
	s_nop 0
	global_load_dword v23, v23, s[72:73] nt
	s_nop 0
	global_load_dword v71, v71, s[72:73] nt
	s_nop 0
	global_load_dword v72, v72, s[72:73] nt
	s_nop 0
	global_load_dword v73, v73, s[72:73] nt
	v_or_b32_e32 v0, s9, v42
	v_or_b32_e32 v77, s9, v45
	v_or_b32_e32 v78, s9, v46
	v_or_b32_e32 v79, s9, v47
	v_or_b32_e32 v80, s9, v48
	v_or_b32_e32 v81, s9, v49
	v_lshlrev_b32_e32 v0, 2, v0
	v_or_b32_e32 v12, s9, v43
	v_or_b32_e32 v13, s9, v44
	v_lshlrev_b32_e32 v77, 2, v77
	v_lshlrev_b32_e32 v78, 2, v78
	v_lshlrev_b32_e32 v79, 2, v79
	v_lshlrev_b32_e32 v80, 2, v80
	v_lshlrev_b32_e32 v81, 2, v81
	v_lshlrev_b32_e32 v12, 2, v12
	v_lshlrev_b32_e32 v13, 2, v13
	global_load_dword v82, v0, s[72:73] nt
	global_load_dword v83, v12, s[72:73] nt
	global_load_dword v84, v13, s[72:73] nt
	s_nop 0
	global_load_dword v77, v77, s[72:73] nt
	s_nop 0
	global_load_dword v78, v78, s[72:73] nt
	s_nop 0
	global_load_dword v79, v79, s[72:73] nt
	s_nop 0
	global_load_dword v80, v80, s[72:73] nt
	s_nop 0
	global_load_dword v81, v81, s[72:73] nt
	v_or_b32_e32 v0, s9, v50
	v_lshlrev_b32_e32 v85, 2, v0
	v_or_b32_e32 v0, s9, v51
	v_lshlrev_b32_e32 v86, 2, v0
	v_or_b32_e32 v0, s9, v52
	v_lshlrev_b32_e32 v87, 2, v0
	v_or_b32_e32 v0, s9, v53
	v_lshlrev_b32_e32 v88, 2, v0
	v_or_b32_e32 v0, s9, v54
	s_and_b32 s6, s20, 0x3e0
	v_lshlrev_b32_e32 v89, 2, v0
	v_or_b32_e32 v0, s9, v55
	v_lshlrev_b32_e32 v90, 2, v0
	v_or_b32_e32 v0, s9, v56
	s_add_i32 s6, s6, s21
	v_lshlrev_b32_e32 v91, 2, v0
	v_add_u32_e32 v0, s6, v26
	v_or_b32_e32 v0, 0xf800, v0
	v_lshl_add_u64 v[12:13], v[0:1], 2, s[72:73]
	global_load_dword v0, v85, s[72:73] nt
	s_nop 0
	global_load_dword v85, v86, s[72:73] nt
	s_nop 0
	global_load_dword v86, v87, s[72:73] nt
	s_nop 0
	global_load_dword v87, v88, s[72:73] nt
	s_nop 0
	global_load_dword v88, v89, s[72:73] nt
	s_nop 0
	global_load_dword v89, v90, s[72:73] nt
	s_nop 0
	global_load_dword v90, v91, s[72:73] nt
	s_nop 0
	global_load_dword v12, v[12:13], off nt
	s_and_b32 s6, s23, 0x3c0
	s_lshl_b32 s6, s6, 1
	s_waitcnt vmcnt(30)
	ds_write2_b32 v62, v19, v20 offset1:66
	s_waitcnt vmcnt(28)
	ds_write2_b32 v62, v21, v14 offset0:132 offset1:198
	s_waitcnt vmcnt(26)
	ds_write2_b32 v64, v15, v16 offset0:8 offset1:74
	s_waitcnt vmcnt(24)
	ds_write2_b32 v64, v17, v18 offset0:140 offset1:206
	s_waitcnt vmcnt(22)
	ds_write2_b32 v65, v74, v75 offset0:16 offset1:82
	s_waitcnt vmcnt(20)
	ds_write2_b32 v65, v76, v22 offset0:148 offset1:214
	s_waitcnt vmcnt(18)
	ds_write2_b32 v66, v23, v71 offset0:24 offset1:90
	s_waitcnt vmcnt(16)
	ds_write2_b32 v66, v72, v73 offset0:156 offset1:222
	s_waitcnt vmcnt(14)
	ds_write2_b32 v67, v82, v83 offset0:32 offset1:98
	s_waitcnt vmcnt(12)
	ds_write2_b32 v67, v84, v77 offset0:164 offset1:230
	s_waitcnt vmcnt(10)
	ds_write2_b32 v68, v78, v79 offset0:40 offset1:106
	s_waitcnt vmcnt(8)
	ds_write2_b32 v68, v80, v81 offset0:172 offset1:238
	s_waitcnt vmcnt(6)
	ds_write2_b32 v69, v0, v85 offset0:48 offset1:114
	s_waitcnt vmcnt(4)
	ds_write2_b32 v69, v86, v87 offset0:180 offset1:246
	s_waitcnt vmcnt(2)
	ds_write2_b32 v70, v88, v89 offset0:56 offset1:122
	s_waitcnt vmcnt(0)
	ds_write2_b32 v70, v90, v12 offset0:188 offset1:254
	s_waitcnt lgkmcnt(0)
	ds_read2_b32 v[16:17], v63 offset0:33 offset1:41
	ds_read2_b32 v[18:19], v63 offset1:8
	ds_read2_b32 v[20:21], v63 offset0:66 offset1:74
	ds_read2_b32 v[22:23], v63 offset0:99 offset1:107
	ds_read2_b32 v[72:73], v63 offset0:132 offset1:140
	ds_read2_b32 v[74:75], v63 offset0:165 offset1:173
	ds_read2_b32 v[76:77], v63 offset0:198 offset1:206
	ds_read2_b32 v[78:79], v63 offset0:231 offset1:239
	v_or_b32_e32 v0, s8, v58
	v_lshl_add_u64 v[80:81], v[6:7], 0, s[6:7]
	v_lshlrev_b32_e32 v0, 11, v0
	s_waitcnt lgkmcnt(6)
	v_cvt_pk_bf16_f32 v12, v18, v16
	s_waitcnt lgkmcnt(4)
	v_cvt_pk_bf16_f32 v13, v20, v22
	s_waitcnt lgkmcnt(2)
	v_cvt_pk_bf16_f32 v14, v72, v74
	s_waitcnt lgkmcnt(0)
; #define LAS __attribute__((address_space(3)))
; __device__ __forceinline__ unsigned pk_bf16(float lo, float hi) { typedef __bf16 b2 __attribute__((ext_vector_type(2))); f32x2 v = {lo, hi}; b2 b = __builtin_convertvector(v, b2); return __builtin_bit_cast(unsigned, b); }
; template <bool MAP> __device__ __forceinline__ void p0_transpose_item(const float* W, int K, int N, u16* WT, LAS float* scr, int item, int lane) {
;     ...
;     const int c = lane & 7;
; #pragma unroll
;     for (int j = 0; j < 4; ++j) { const int n = (lane >> 3) + 8 * j; const LAS float* s = scr + (8 * c) * 33 + n;
;         u32x4 o; o.x = pk_bf16(s[0 * 33], s[1 * 33]); o.y = pk_bf16(s[2 * 33], s[3 * 33]); o.z = pk_bf16(s[4 * 33], s[5 * 33]); o.w = pk_bf16(s[6 * 33], s[7 * 33]);
;         const int r = MAP ? wt_row_of_col(n0 + n) : (n0 + n);
;         *(u32x4*)(WT + (size_t)r * K + k0 + 8 * c) = o; }
;     asm volatile("s_waitcnt lgkmcnt(0)" ::: "memory");
	v_cvt_pk_bf16_f32 v15, v76, v78
	v_lshl_add_u64 v[82:83], v[80:81], 0, v[0:1]
	global_store_dwordx4 v[82:83], v[12:15], off
	v_or_b32_e32 v0, s8, v59
	v_lshlrev_b32_e32 v0, 11, v0
	v_cvt_pk_bf16_f32 v12, v19, v17
	v_cvt_pk_bf16_f32 v13, v21, v23
	v_cvt_pk_bf16_f32 v14, v73, v75
	v_cvt_pk_bf16_f32 v15, v77, v79
	ds_read2_b32 v[18:19], v63 offset0:49 offset1:57
	ds_read2_b32 v[20:21], v63 offset0:16 offset1:24
	ds_read2_b32 v[22:23], v63 offset0:82 offset1:90
	ds_read2_b32 v[72:73], v63 offset0:115 offset1:123
	ds_read2_b32 v[74:75], v63 offset0:148 offset1:156
	ds_read2_b32 v[76:77], v63 offset0:181 offset1:189
	ds_read2_b32 v[78:79], v63 offset0:214 offset1:222
	ds_read2_b32 v[82:83], v63 offset0:247 offset1:255
	v_lshl_add_u64 v[16:17], v[80:81], 0, v[0:1]
	v_or_b32_e32 v0, s8, v60
	v_lshlrev_b32_e32 v0, 11, v0
	global_store_dwordx4 v[16:17], v[12:15], off
	v_lshl_add_u64 v[16:17], v[80:81], 0, v[0:1]
	v_or_b32_e32 v0, s8, v61
	s_waitcnt lgkmcnt(6)
	v_cvt_pk_bf16_f32 v12, v20, v18
	s_waitcnt lgkmcnt(4)
	v_cvt_pk_bf16_f32 v13, v22, v72
	s_waitcnt lgkmcnt(2)
	v_cvt_pk_bf16_f32 v14, v74, v76
	s_waitcnt lgkmcnt(0)
	v_cvt_pk_bf16_f32 v15, v78, v82
	v_lshlrev_b32_e32 v0, 11, v0
	global_store_dwordx4 v[16:17], v[12:15], off
	v_lshl_add_u64 v[16:17], v[80:81], 0, v[0:1]
	s_mov_b64 s[8:9], 0
	v_cvt_pk_bf16_f32 v12, v21, v19
	v_cvt_pk_bf16_f32 v13, v23, v73
	v_cvt_pk_bf16_f32 v14, v75, v77
	v_cvt_pk_bf16_f32 v15, v79, v83
	global_store_dwordx4 v[16:17], v[12:15], off
	s_waitcnt lgkmcnt(0)
.LBB0_28:
	s_andn2_b64 vcc, exec, s[8:9]
	s_cbranch_vccnz .LBB0_30
; #define LAS __attribute__((address_space(3)))
; __device__ __forceinline__ unsigned pk_bf16(float lo, float hi) { typedef __bf16 b2 __attribute__((ext_vector_type(2))); f32x2 v = {lo, hi}; b2 b = __builtin_convertvector(v, b2); return __builtin_bit_cast(unsigned, b); }
; template <bool MAP> __device__ __forceinline__ void p0_transpose_item(const float* W, int K, int N, u16* WT, LAS float* scr, int item, int lane) {
;     const int nblk = N / 32, kb = item / nblk, nb = item % nblk, k0 = 64 * kb, n0 = 32 * nb;
;     float tv[32];
; #pragma unroll
;     for (int i = 0; i < 32; ++i) tv[i] = W[(size_t)(k0 + 2 * i + (lane >> 5)) * N + n0 + (lane & 31)];
; #pragma unroll
;     for (int i = 0; i < 32; ++i) scr[(2 * i + (lane >> 5)) * 33 + (lane & 31)] = tv[i];
;     asm volatile("s_waitcnt lgkmcnt(0)" ::: "memory");
;     const int c = lane & 7;
; #pragma unroll
;     for (int j = 0; j < 4; ++j) { const int n = (lane >> 3) + 8 * j; const LAS float* s = scr + (8 * c) * 33 + n;
;         u32x4 o; o.x = pk_bf16(s[0 * 33], s[1 * 33]); o.y = pk_bf16(s[2 * 33], s[3 * 33]); o.z = pk_bf16(s[4 * 33], s[5 * 33]); o.w = pk_bf16(s[6 * 33], s[7 * 33]);
;         const int r = MAP ? wt_row_of_col(n0 + n) : (n0 + n);
;         *(u32x4*)(WT + (size_t)r * K + k0 + 8 * c) = o; }
;     asm volatile("s_waitcnt lgkmcnt(0)" ::: "memory");
; __device__ __forceinline__ void p0_prologue(const Ptrs& P, LAS unsigned char* lds, int vcu, int G) {
;     ...
;         if (r < I_B) { p0_transpose_item<false>(P.wb, 512, 1024, (u16*)(P.ws + WS_WB), scr, r, lane); continue; } r -= I_B;
	s_add_i32 s8, s18, 0xfffd0000
	s_add_i32 s9, s21, 0xc80000
	s_and_b32 s8, s8, 0x3e0
	s_and_b32 s9, s9, 0xf0000
	s_or_b32 s9, s8, s9
	v_or_b32_e32 v0, s9, v26
	v_or_b32_e32 v14, s9, v29
	v_or_b32_e32 v15, s9, v30
	v_or_b32_e32 v16, s9, v31
	v_or_b32_e32 v17, s9, v32
	v_or_b32_e32 v18, s9, v33
	v_lshlrev_b32_e32 v0, 2, v0
	v_or_b32_e32 v12, s9, v27
	v_or_b32_e32 v13, s9, v28
	v_lshlrev_b32_e32 v14, 2, v14
	v_lshlrev_b32_e32 v15, 2, v15
	v_lshlrev_b32_e32 v16, 2, v16
	v_lshlrev_b32_e32 v17, 2, v17
	v_lshlrev_b32_e32 v18, 2, v18
	v_lshlrev_b32_e32 v12, 2, v12
	v_lshlrev_b32_e32 v13, 2, v13
	global_load_dword v19, v0, s[70:71] nt
	global_load_dword v20, v12, s[70:71] nt
	global_load_dword v21, v13, s[70:71] nt
	s_nop 0
	global_load_dword v14, v14, s[70:71] nt
	s_nop 0
	global_load_dword v15, v15, s[70:71] nt
	s_nop 0
	global_load_dword v16, v16, s[70:71] nt
	s_nop 0
	global_load_dword v17, v17, s[70:71] nt
	s_nop 0
	global_load_dword v18, v18, s[70:71] nt
	v_or_b32_e32 v0, s9, v34
	v_or_b32_e32 v22, s9, v37
	v_or_b32_e32 v23, s9, v38
	v_or_b32_e32 v71, s9, v39
	v_or_b32_e32 v72, s9, v40
	v_or_b32_e32 v73, s9, v41
	v_lshlrev_b32_e32 v0, 2, v0
	v_or_b32_e32 v12, s9, v35
	v_or_b32_e32 v13, s9, v36
	v_lshlrev_b32_e32 v22, 2, v22
	v_lshlrev_b32_e32 v23, 2, v23
	v_lshlrev_b32_e32 v71, 2, v71
	v_lshlrev_b32_e32 v72, 2, v72
	v_lshlrev_b32_e32 v73, 2, v73
	v_lshlrev_b32_e32 v12, 2, v12
	v_lshlrev_b32_e32 v13, 2, v13
	global_load_dword v74, v0, s[70:71] nt
	global_load_dword v75, v12, s[70:71] nt
	global_load_dword v76, v13, s[70:71] nt
	s_nop 0
	global_load_dword v22, v22, s[70:71] nt
	s_nop 0
	global_load_dword v23, v23, s[70:71] nt
	s_nop 0
	global_load_dword v71, v71, s[70:71] nt
	s_nop 0
	global_load_dword v72, v72, s[70:71] nt
	s_nop 0
	global_load_dword v73, v73, s[70:71] nt
	v_or_b32_e32 v0, s9, v42
	v_or_b32_e32 v77, s9, v45
	v_or_b32_e32 v78, s9, v46
	v_or_b32_e32 v79, s9, v47
	v_or_b32_e32 v80, s9, v48
	v_or_b32_e32 v81, s9, v49
	v_lshlrev_b32_e32 v0, 2, v0
	v_or_b32_e32 v12, s9, v43
	v_or_b32_e32 v13, s9, v44
	v_lshlrev_b32_e32 v77, 2, v77
	v_lshlrev_b32_e32 v78, 2, v78
	v_lshlrev_b32_e32 v79, 2, v79
	v_lshlrev_b32_e32 v80, 2, v80
	v_lshlrev_b32_e32 v81, 2, v81
	v_lshlrev_b32_e32 v12, 2, v12
	v_lshlrev_b32_e32 v13, 2, v13
	global_load_dword v82, v0, s[70:71] nt
	global_load_dword v83, v12, s[70:71] nt
	global_load_dword v84, v13, s[70:71] nt
	s_nop 0
	global_load_dword v77, v77, s[70:71] nt
	s_nop 0
	global_load_dword v78, v78, s[70:71] nt
	s_nop 0
	global_load_dword v79, v79, s[70:71] nt
	s_nop 0
	global_load_dword v80, v80, s[70:71] nt
	s_nop 0
	global_load_dword v81, v81, s[70:71] nt
	v_or_b32_e32 v0, s9, v50
	v_lshlrev_b32_e32 v85, 2, v0
	v_or_b32_e32 v0, s9, v51
	v_lshlrev_b32_e32 v86, 2, v0
	v_or_b32_e32 v0, s9, v52
	v_lshlrev_b32_e32 v87, 2, v0
	v_or_b32_e32 v0, s9, v53
	v_lshlrev_b32_e32 v88, 2, v0
	v_or_b32_e32 v0, s9, v54
	s_and_b32 s6, s25, 0x3e0
	v_lshlrev_b32_e32 v89, 2, v0
	v_or_b32_e32 v0, s9, v55
	v_lshlrev_b32_e32 v90, 2, v0
	v_or_b32_e32 v0, s9, v56
	s_add_i32 s6, s6, s21
	v_lshlrev_b32_e32 v91, 2, v0
	v_add_u32_e32 v0, s6, v26
	v_add_u32_e32 v0, 0x80000, v0
	v_or_b32_e32 v0, 0xf800, v0
	v_lshl_add_u64 v[12:13], v[0:1], 2, s[70:71]
	global_load_dword v0, v85, s[70:71] nt
	s_nop 0
	global_load_dword v85, v86, s[70:71] nt
	s_nop 0
	global_load_dword v86, v87, s[70:71] nt
	s_nop 0
	global_load_dword v87, v88, s[70:71] nt
	s_nop 0
	global_load_dword v88, v89, s[70:71] nt
	s_nop 0
	global_load_dword v89, v90, s[70:71] nt
	s_nop 0
	global_load_dword v90, v91, s[70:71] nt
	s_nop 0
	global_load_dword v12, v[12:13], off nt
	s_add_i32 s6, s23, 0x200
	s_and_b32 s6, s6, 0x3c0
	s_lshl_b32 s6, s6, 1
	s_waitcnt vmcnt(30)
	ds_write2_b32 v62, v19, v20 offset1:66
	s_waitcnt vmcnt(28)
	ds_write2_b32 v62, v21, v14 offset0:132 offset1:198
	s_waitcnt vmcnt(26)
	ds_write2_b32 v64, v15, v16 offset0:8 offset1:74
	s_waitcnt vmcnt(24)
	ds_write2_b32 v64, v17, v18 offset0:140 offset1:206
	s_waitcnt vmcnt(22)
	ds_write2_b32 v65, v74, v75 offset0:16 offset1:82
	s_waitcnt vmcnt(20)
	ds_write2_b32 v65, v76, v22 offset0:148 offset1:214
	s_waitcnt vmcnt(18)
	ds_write2_b32 v66, v23, v71 offset0:24 offset1:90
	s_waitcnt vmcnt(16)
	ds_write2_b32 v66, v72, v73 offset0:156 offset1:222
	s_waitcnt vmcnt(14)
	ds_write2_b32 v67, v82, v83 offset0:32 offset1:98
	s_waitcnt vmcnt(12)
	ds_write2_b32 v67, v84, v77 offset0:164 offset1:230
	s_waitcnt vmcnt(10)
	ds_write2_b32 v68, v78, v79 offset0:40 offset1:106
	s_waitcnt vmcnt(8)
	ds_write2_b32 v68, v80, v81 offset0:172 offset1:238
	s_waitcnt vmcnt(6)
	ds_write2_b32 v69, v0, v85 offset0:48 offset1:114
	s_waitcnt vmcnt(4)
	ds_write2_b32 v69, v86, v87 offset0:180 offset1:246
	s_waitcnt vmcnt(2)
	ds_write2_b32 v70, v88, v89 offset0:56 offset1:122
	s_waitcnt vmcnt(0)
	ds_write2_b32 v70, v90, v12 offset0:188 offset1:254
	s_waitcnt lgkmcnt(0)
	ds_read2_b32 v[16:17], v63 offset0:33 offset1:41
	ds_read2_b32 v[18:19], v63 offset1:8
	ds_read2_b32 v[20:21], v63 offset0:66 offset1:74
	ds_read2_b32 v[22:23], v63 offset0:99 offset1:107
	ds_read2_b32 v[72:73], v63 offset0:132 offset1:140
	ds_read2_b32 v[74:75], v63 offset0:165 offset1:173
	ds_read2_b32 v[76:77], v63 offset0:198 offset1:206
	ds_read2_b32 v[78:79], v63 offset0:231 offset1:239
	v_or_b32_e32 v0, s8, v58
	v_lshl_add_u64 v[80:81], v[8:9], 0, s[6:7]
	v_lshlrev_b32_e32 v0, 10, v0
	s_waitcnt lgkmcnt(6)
	v_cvt_pk_bf16_f32 v12, v18, v16
	s_waitcnt lgkmcnt(4)
	v_cvt_pk_bf16_f32 v13, v20, v22
	s_waitcnt lgkmcnt(2)
	v_cvt_pk_bf16_f32 v14, v72, v74
	s_waitcnt lgkmcnt(0)
	v_cvt_pk_bf16_f32 v15, v76, v78
	v_lshl_add_u64 v[82:83], v[80:81], 0, v[0:1]
	global_store_dwordx4 v[82:83], v[12:15], off
	v_or_b32_e32 v0, s8, v59
	v_lshlrev_b32_e32 v0, 10, v0
	v_cvt_pk_bf16_f32 v12, v19, v17
	v_cvt_pk_bf16_f32 v13, v21, v23
	v_cvt_pk_bf16_f32 v14, v73, v75
	v_cvt_pk_bf16_f32 v15, v77, v79
	ds_read2_b32 v[18:19], v63 offset0:49 offset1:57
	ds_read2_b32 v[20:21], v63 offset0:16 offset1:24
	ds_read2_b32 v[22:23], v63 offset0:82 offset1:90
	ds_read2_b32 v[72:73], v63 offset0:115 offset1:123
	ds_read2_b32 v[74:75], v63 offset0:148 offset1:156
	ds_read2_b32 v[76:77], v63 offset0:181 offset1:189
	ds_read2_b32 v[78:79], v63 offset0:214 offset1:222
	ds_read2_b32 v[82:83], v63 offset0:247 offset1:255
	v_lshl_add_u64 v[16:17], v[80:81], 0, v[0:1]
	v_or_b32_e32 v0, s8, v60
	v_lshlrev_b32_e32 v0, 10, v0
	global_store_dwordx4 v[16:17], v[12:15], off
	v_lshl_add_u64 v[16:17], v[80:81], 0, v[0:1]
	v_or_b32_e32 v0, s8, v61
	s_waitcnt lgkmcnt(6)
	v_cvt_pk_bf16_f32 v12, v20, v18
	s_waitcnt lgkmcnt(4)
	v_cvt_pk_bf16_f32 v13, v22, v72
	s_waitcnt lgkmcnt(2)
	v_cvt_pk_bf16_f32 v14, v74, v76
	s_waitcnt lgkmcnt(0)
	v_cvt_pk_bf16_f32 v15, v78, v82
	v_lshlrev_b32_e32 v0, 10, v0
	global_store_dwordx4 v[16:17], v[12:15], off
	v_lshl_add_u64 v[16:17], v[80:81], 0, v[0:1]
	s_nop 0
	v_cvt_pk_bf16_f32 v12, v21, v19
	v_cvt_pk_bf16_f32 v13, v23, v73
	v_cvt_pk_bf16_f32 v14, v75, v77
	v_cvt_pk_bf16_f32 v15, v79, v83
	global_store_dwordx4 v[16:17], v[12:15], off
	s_waitcnt lgkmcnt(0)

; __device__ __forceinline__ void p0_prologue(const Ptrs& P, LAS unsigned char* lds, int vcu, int G) {
;     ...
;     for (int it = gw; it < NITEMS; it += NGW) {
;         int r = it;
;         if (r < I_IN) { p0_transpose_item<true>(P.w_in, 1024, NIN, (u16*)(P.ws + WS_WT), scr, r, lane); continue; } r -= I_IN;
;         if (r < I_A) { p0_transpose_item<false>(P.wa, 1024, 1024, (u16*)(P.ws + WS_WA), scr, r, lane); continue; } r -= I_A;
;         if (r < I_B) { p0_transpose_item<false>(P.wb, 512, 1024, (u16*)(P.ws + WS_WB), scr, r, lane); continue; } r -= I_B;
;         p0_transpose_item<false>(P.wo, 1024, 1024, (u16*)(P.ws + WS_WO), scr, r, lane);
.LBB0_31:
	s_andn2_b64 vcc, exec, s[8:9]
	s_cbranch_vccnz .LBB0_33
; #define LAS __attribute__((address_space(3)))
; __device__ __forceinline__ unsigned pk_bf16(float lo, float hi) { typedef __bf16 b2 __attribute__((ext_vector_type(2))); f32x2 v = {lo, hi}; b2 b = __builtin_convertvector(v, b2); return __builtin_bit_cast(unsigned, b); }
; template <bool MAP> __device__ __forceinline__ void p0_transpose_item(const float* W, int K, int N, u16* WT, LAS float* scr, int item, int lane) {
;     const int nblk = N / 32, kb = item / nblk, nb = item % nblk, k0 = 64 * kb, n0 = 32 * nb;
;     float tv[32];
; #pragma unroll
;     for (int i = 0; i < 32; ++i) tv[i] = W[(size_t)(k0 + 2 * i + (lane >> 5)) * N + n0 + (lane & 31)];
; #pragma unroll
;     for (int i = 0; i < 32; ++i) scr[(2 * i + (lane >> 5)) * 33 + (lane & 31)] = tv[i];
;     asm volatile("s_waitcnt lgkmcnt(0)" ::: "memory");
;     const int c = lane & 7;
; #pragma unroll
;     for (int j = 0; j < 4; ++j) { const int n = (lane >> 3) + 8 * j; const LAS float* s = scr + (8 * c) * 33 + n;
;         u32x4 o; o.x = pk_bf16(s[0 * 33], s[1 * 33]); o.y = pk_bf16(s[2 * 33], s[3 * 33]); o.z = pk_bf16(s[4 * 33], s[5 * 33]); o.w = pk_bf16(s[6 * 33], s[7 * 33]);
;         const int r = MAP ? wt_row_of_col(n0 + n) : (n0 + n);
;         *(u32x4*)(WT + (size_t)r * K + k0 + 8 * c) = o; }
;     asm volatile("s_waitcnt lgkmcnt(0)" ::: "memory");
	s_add_i32 s8, s18, 0xfffd4000
	s_add_i32 s9, s21, 0xc80000
	s_and_b32 s8, s8, 0x3e0
	s_and_b32 s9, s9, 0xf0000
	s_or_b32 s9, s8, s9
	v_or_b32_e32 v0, s9, v26
	v_or_b32_e32 v14, s9, v29
	v_or_b32_e32 v15, s9, v30
	v_or_b32_e32 v16, s9, v31
	v_or_b32_e32 v17, s9, v32
	v_or_b32_e32 v18, s9, v33
	v_lshlrev_b32_e32 v0, 2, v0
	v_or_b32_e32 v12, s9, v27
	v_or_b32_e32 v13, s9, v28
	v_lshlrev_b32_e32 v14, 2, v14
	v_lshlrev_b32_e32 v15, 2, v15
	v_lshlrev_b32_e32 v16, 2, v16
	v_lshlrev_b32_e32 v17, 2, v17
	v_lshlrev_b32_e32 v18, 2, v18
	v_lshlrev_b32_e32 v12, 2, v12
	v_lshlrev_b32_e32 v13, 2, v13
	global_load_dword v19, v0, s[68:69] nt
	global_load_dword v20, v12, s[68:69] nt
	global_load_dword v21, v13, s[68:69] nt
	s_nop 0
	global_load_dword v14, v14, s[68:69] nt
	s_nop 0
	global_load_dword v15, v15, s[68:69] nt
	s_nop 0
	global_load_dword v16, v16, s[68:69] nt
	s_nop 0
	global_load_dword v17, v17, s[68:69] nt
	s_nop 0
	global_load_dword v18, v18, s[68:69] nt
	v_or_b32_e32 v0, s9, v34
	v_or_b32_e32 v22, s9, v37
	v_or_b32_e32 v23, s9, v38
	v_or_b32_e32 v71, s9, v39
	v_or_b32_e32 v72, s9, v40
	v_or_b32_e32 v73, s9, v41
	v_lshlrev_b32_e32 v0, 2, v0
	v_or_b32_e32 v12, s9, v35
	v_or_b32_e32 v13, s9, v36
	v_lshlrev_b32_e32 v22, 2, v22
	v_lshlrev_b32_e32 v23, 2, v23
	v_lshlrev_b32_e32 v71, 2, v71
	v_lshlrev_b32_e32 v72, 2, v72
	v_lshlrev_b32_e32 v73, 2, v73
	v_lshlrev_b32_e32 v12, 2, v12
	v_lshlrev_b32_e32 v13, 2, v13
	global_load_dword v74, v0, s[68:69] nt
	global_load_dword v75, v12, s[68:69] nt
	global_load_dword v76, v13, s[68:69] nt
	s_nop 0
	global_load_dword v22, v22, s[68:69] nt
	s_nop 0
	global_load_dword v23, v23, s[68:69] nt
	s_nop 0
	global_load_dword v71, v71, s[68:69] nt
	s_nop 0
	global_load_dword v72, v72, s[68:69] nt
	s_nop 0
	global_load_dword v73, v73, s[68:69] nt
	v_or_b32_e32 v0, s9, v42
	v_or_b32_e32 v77, s9, v45
	v_or_b32_e32 v78, s9, v46
	v_or_b32_e32 v79, s9, v47
	v_or_b32_e32 v80, s9, v48
	v_or_b32_e32 v81, s9, v49
	v_lshlrev_b32_e32 v0, 2, v0
	v_or_b32_e32 v12, s9, v43
	v_or_b32_e32 v13, s9, v44
	v_lshlrev_b32_e32 v77, 2, v77
	v_lshlrev_b32_e32 v78, 2, v78
	v_lshlrev_b32_e32 v79, 2, v79
	v_lshlrev_b32_e32 v80, 2, v80
	v_lshlrev_b32_e32 v81, 2, v81
	v_lshlrev_b32_e32 v12, 2, v12
	v_lshlrev_b32_e32 v13, 2, v13
	global_load_dword v82, v0, s[68:69] nt
	global_load_dword v83, v12, s[68:69] nt
	global_load_dword v84, v13, s[68:69] nt
	s_nop 0
	global_load_dword v77, v77, s[68:69] nt
	s_nop 0
	global_load_dword v78, v78, s[68:69] nt
	s_nop 0
	global_load_dword v79, v79, s[68:69] nt
	s_nop 0
	global_load_dword v80, v80, s[68:69] nt
	s_nop 0
	global_load_dword v81, v81, s[68:69] nt
	v_or_b32_e32 v0, s9, v50
	v_lshlrev_b32_e32 v85, 2, v0
	v_or_b32_e32 v0, s9, v51
	v_lshlrev_b32_e32 v86, 2, v0
	v_or_b32_e32 v0, s9, v52
	v_lshlrev_b32_e32 v87, 2, v0
	v_or_b32_e32 v0, s9, v53
	v_lshlrev_b32_e32 v88, 2, v0
	v_or_b32_e32 v0, s9, v54
	s_and_b32 s6, s26, 0x3e0
	v_lshlrev_b32_e32 v89, 2, v0
	v_or_b32_e32 v0, s9, v55
	v_lshlrev_b32_e32 v90, 2, v0
	v_or_b32_e32 v0, s9, v56
	s_add_i32 s6, s6, s21
	v_lshlrev_b32_e32 v91, 2, v0
	v_add_u32_e32 v0, s6, v26
	v_add_u32_e32 v0, 0x180000, v0
	v_or_b32_e32 v0, 0xf800, v0
	v_lshl_add_u64 v[12:13], v[0:1], 2, s[68:69]
	global_load_dword v0, v85, s[68:69] nt
	s_nop 0
	global_load_dword v85, v86, s[68:69] nt
	s_nop 0
	global_load_dword v86, v87, s[68:69] nt
	s_nop 0
	global_load_dword v87, v88, s[68:69] nt
	s_nop 0
	global_load_dword v88, v89, s[68:69] nt
	s_nop 0
	global_load_dword v89, v90, s[68:69] nt
	s_nop 0
	global_load_dword v90, v91, s[68:69] nt
	s_nop 0
	global_load_dword v12, v[12:13], off nt
	s_add_i32 s6, s23, 0x600
	s_and_b32 s6, s6, 0x3c0
	s_lshl_b32 s6, s6, 1
	s_waitcnt vmcnt(30)
	ds_write2_b32 v62, v19, v20 offset1:66
	s_waitcnt vmcnt(28)
	ds_write2_b32 v62, v21, v14 offset0:132 offset1:198
	s_waitcnt vmcnt(26)
	ds_write2_b32 v64, v15, v16 offset0:8 offset1:74
	s_waitcnt vmcnt(24)
	ds_write2_b32 v64, v17, v18 offset0:140 offset1:206
	s_waitcnt vmcnt(22)
	ds_write2_b32 v65, v74, v75 offset0:16 offset1:82
	s_waitcnt vmcnt(20)
	ds_write2_b32 v65, v76, v22 offset0:148 offset1:214
	s_waitcnt vmcnt(18)
	ds_write2_b32 v66, v23, v71 offset0:24 offset1:90
	s_waitcnt vmcnt(16)
	ds_write2_b32 v66, v72, v73 offset0:156 offset1:222
	s_waitcnt vmcnt(14)
	ds_write2_b32 v67, v82, v83 offset0:32 offset1:98
	s_waitcnt vmcnt(12)
	ds_write2_b32 v67, v84, v77 offset0:164 offset1:230
	s_waitcnt vmcnt(10)
	ds_write2_b32 v68, v78, v79 offset0:40 offset1:106
	s_waitcnt vmcnt(8)
	ds_write2_b32 v68, v80, v81 offset0:172 offset1:238
	s_waitcnt vmcnt(6)
	ds_write2_b32 v69, v0, v85 offset0:48 offset1:114
	s_waitcnt vmcnt(4)
	ds_write2_b32 v69, v86, v87 offset0:180 offset1:246
	s_waitcnt vmcnt(2)
	ds_write2_b32 v70, v88, v89 offset0:56 offset1:122
	s_waitcnt vmcnt(0)
	ds_write2_b32 v70, v90, v12 offset0:188 offset1:254
	s_waitcnt lgkmcnt(0)
	ds_read2_b32 v[16:17], v63 offset0:33 offset1:41
	ds_read2_b32 v[18:19], v63 offset1:8
	ds_read2_b32 v[20:21], v63 offset0:66 offset1:74
	ds_read2_b32 v[22:23], v63 offset0:99 offset1:107
	ds_read2_b32 v[72:73], v63 offset0:132 offset1:140
	ds_read2_b32 v[74:75], v63 offset0:165 offset1:173
	ds_read2_b32 v[76:77], v63 offset0:198 offset1:206
	ds_read2_b32 v[78:79], v63 offset0:231 offset1:239
	v_or_b32_e32 v0, s8, v58
	v_lshl_add_u64 v[80:81], v[10:11], 0, s[6:7]
	v_lshlrev_b32_e32 v0, 11, v0
	s_waitcnt lgkmcnt(6)
	v_cvt_pk_bf16_f32 v12, v18, v16
	s_waitcnt lgkmcnt(4)
	v_cvt_pk_bf16_f32 v13, v20, v22
	s_waitcnt lgkmcnt(2)
	v_cvt_pk_bf16_f32 v14, v72, v74
	s_waitcnt lgkmcnt(0)
	v_cvt_pk_bf16_f32 v15, v76, v78
	v_lshl_add_u64 v[82:83], v[80:81], 0, v[0:1]
	global_store_dwordx4 v[82:83], v[12:15], off
	v_or_b32_e32 v0, s8, v59
	v_lshlrev_b32_e32 v0, 11, v0
	v_cvt_pk_bf16_f32 v12, v19, v17
	v_cvt_pk_bf16_f32 v13, v21, v23
	v_cvt_pk_bf16_f32 v14, v73, v75
	v_cvt_pk_bf16_f32 v15, v77, v79
	ds_read2_b32 v[18:19], v63 offset0:49 offset1:57
	ds_read2_b32 v[20:21], v63 offset0:16 offset1:24
	ds_read2_b32 v[22:23], v63 offset0:82 offset1:90
	ds_read2_b32 v[72:73], v63 offset0:115 offset1:123
	ds_read2_b32 v[74:75], v63 offset0:148 offset1:156
	ds_read2_b32 v[76:77], v63 offset0:181 offset1:189
	ds_read2_b32 v[78:79], v63 offset0:214 offset1:222
	ds_read2_b32 v[82:83], v63 offset0:247 offset1:255
	v_lshl_add_u64 v[16:17], v[80:81], 0, v[0:1]
	v_or_b32_e32 v0, s8, v60
	v_lshlrev_b32_e32 v0, 11, v0
	global_store_dwordx4 v[16:17], v[12:15], off
	v_lshl_add_u64 v[16:17], v[80:81], 0, v[0:1]
	v_or_b32_e32 v0, s8, v61
	s_waitcnt lgkmcnt(6)
	v_cvt_pk_bf16_f32 v12, v20, v18
	s_waitcnt lgkmcnt(4)
	v_cvt_pk_bf16_f32 v13, v22, v72
	s_waitcnt lgkmcnt(2)
	v_cvt_pk_bf16_f32 v14, v74, v76
	s_waitcnt lgkmcnt(0)
	v_cvt_pk_bf16_f32 v15, v78, v82
	v_lshlrev_b32_e32 v0, 11, v0
	global_store_dwordx4 v[16:17], v[12:15], off
	v_lshl_add_u64 v[16:17], v[80:81], 0, v[0:1]
	s_nop 0
	v_cvt_pk_bf16_f32 v12, v21, v19
	v_cvt_pk_bf16_f32 v13, v23, v73
	v_cvt_pk_bf16_f32 v14, v75, v77
	v_cvt_pk_bf16_f32 v15, v79, v83
	global_store_dwordx4 v[16:17], v[12:15], off
	s_waitcnt lgkmcnt(0)

; #define LAS __attribute__((address_space(3)))
; __device__ __forceinline__ unsigned pk_bf16(float lo, float hi) { typedef __bf16 b2 __attribute__((ext_vector_type(2))); f32x2 v = {lo, hi}; b2 b = __builtin_convertvector(v, b2); return __builtin_bit_cast(unsigned, b); }
; __device__ __forceinline__ int wt_row_of_col(int n) {
;     if (n < 4096) return n;
;     if (n >= 9216) return 4096 + (n - 9216);
;     int a = n - 4096;
;     if (a < 3072) { const int e = a & 63; a = (a - e) + (e < 32 ? 2 * e : 2 * (e - 32) + 1); }
;     return 6144 + a;
; }
; template <bool MAP> __device__ __forceinline__ void p0_transpose_item(const float* W, int K, int N, u16* WT, LAS float* scr, int item, int lane) {
;     const int nblk = N / 32, kb = item / nblk, nb = item % nblk, k0 = 64 * kb, n0 = 32 * nb;
;     float tv[32];
; #pragma unroll
;     for (int i = 0; i < 32; ++i) tv[i] = W[(size_t)(k0 + 2 * i + (lane >> 5)) * N + n0 + (lane & 31)];
; #pragma unroll
;     for (int i = 0; i < 32; ++i) scr[(2 * i + (lane >> 5)) * 33 + (lane & 31)] = tv[i];
;     asm volatile("s_waitcnt lgkmcnt(0)" ::: "memory");
;     const int c = lane & 7;
; #pragma unroll
;     for (int j = 0; j < 4; ++j) { const int n = (lane >> 3) + 8 * j; const LAS float* s = scr + (8 * c) * 33 + n;
;         u32x4 o; o.x = pk_bf16(s[0 * 33], s[1 * 33]); o.y = pk_bf16(s[2 * 33], s[3 * 33]); o.z = pk_bf16(s[4 * 33], s[5 * 33]); o.w = pk_bf16(s[6 * 33], s[7 * 33]);
;         const int r = MAP ? wt_row_of_col(n0 + n) : (n0 + n);
;         *(u32x4*)(WT + (size_t)r * K + k0 + 8 * c) = o; }
.LBB0_34:
	s_andn2_b64 vcc, exec, s[8:9]
	s_cbranch_vccnz .LBB0_23
	s_mul_hi_i32 s6, s28, 0x2e8ba2e9
	s_lshr_b32 s8, s6, 31
	s_ashr_i32 s6, s6, 6
	s_add_i32 s6, s6, s8
	s_mul_i32 s8, s6, 0xffffd400
	s_lshl_b32 s10, s6, 6
	s_add_i32 s8, s18, s8
	v_or_b32_e32 v0, s10, v57
	s_ashr_i32 s9, s8, 31
	v_lshl_add_u64 v[12:13], s[8:9], 2, v[2:3]
	v_or_b32_e32 v71, 10, v0
	v_mad_i64_i32 v[72:73], s[12:13], v71, s1, v[12:13]
	v_or_b32_e32 v71, 12, v0
	v_or_b32_e32 v16, 2, v0
	v_or_b32_e32 v18, 4, v0
	v_or_b32_e32 v20, 6, v0
	v_or_b32_e32 v22, 8, v0
	v_mad_i64_i32 v[74:75], s[12:13], v71, s1, v[12:13]
	v_or_b32_e32 v71, 14, v0
	v_mad_i64_i32 v[14:15], s[12:13], v0, s1, v[12:13]
	v_mad_i64_i32 v[16:17], s[12:13], v16, s1, v[12:13]
	v_mad_i64_i32 v[18:19], s[12:13], v18, s1, v[12:13]
	v_mad_i64_i32 v[20:21], s[12:13], v20, s1, v[12:13]
	v_mad_i64_i32 v[22:23], s[12:13], v22, s1, v[12:13]
	v_mad_i64_i32 v[76:77], s[12:13], v71, s1, v[12:13]
	global_load_dword v71, v[14:15], off nt
	global_load_dword v78, v[16:17], off nt
	global_load_dword v79, v[18:19], off nt
	global_load_dword v80, v[20:21], off nt
	global_load_dword v81, v[22:23], off nt
	global_load_dword v82, v[72:73], off nt
	global_load_dword v83, v[74:75], off nt
	global_load_dword v84, v[76:77], off nt
	v_or_b32_e32 v14, 16, v0
	v_or_b32_e32 v16, 18, v0
	v_or_b32_e32 v18, 20, v0
	v_or_b32_e32 v20, 22, v0
	v_or_b32_e32 v22, 24, v0
	v_or_b32_e32 v72, 26, v0
	v_or_b32_e32 v74, 28, v0
	v_or_b32_e32 v76, 30, v0
	v_mad_i64_i32 v[14:15], s[12:13], v14, s1, v[12:13]
	v_mad_i64_i32 v[16:17], s[12:13], v16, s1, v[12:13]
	v_mad_i64_i32 v[18:19], s[12:13], v18, s1, v[12:13]
	v_mad_i64_i32 v[20:21], s[12:13], v20, s1, v[12:13]
	v_mad_i64_i32 v[22:23], s[12:13], v22, s1, v[12:13]
	v_mad_i64_i32 v[72:73], s[12:13], v72, s1, v[12:13]
	v_mad_i64_i32 v[74:75], s[12:13], v74, s1, v[12:13]
	v_mad_i64_i32 v[76:77], s[12:13], v76, s1, v[12:13]
	global_load_dword v85, v[14:15], off nt
	global_load_dword v86, v[16:17], off nt
	global_load_dword v87, v[18:19], off nt
	global_load_dword v88, v[20:21], off nt
	global_load_dword v89, v[22:23], off nt
	global_load_dword v90, v[72:73], off nt
	global_load_dword v91, v[74:75], off nt
	global_load_dword v92, v[76:77], off nt
	v_or_b32_e32 v14, 32, v0
	v_or_b32_e32 v16, 34, v0
	v_or_b32_e32 v18, 36, v0
	v_or_b32_e32 v20, 38, v0
	v_or_b32_e32 v22, 40, v0
	v_or_b32_e32 v72, 42, v0
	v_or_b32_e32 v74, 44, v0
	v_or_b32_e32 v76, 46, v0
	v_mad_i64_i32 v[14:15], s[12:13], v14, s1, v[12:13]
	v_mad_i64_i32 v[16:17], s[12:13], v16, s1, v[12:13]
	v_mad_i64_i32 v[18:19], s[12:13], v18, s1, v[12:13]
	v_mad_i64_i32 v[20:21], s[12:13], v20, s1, v[12:13]
	v_mad_i64_i32 v[22:23], s[12:13], v22, s1, v[12:13]
	v_mad_i64_i32 v[72:73], s[12:13], v72, s1, v[12:13]
	v_mad_i64_i32 v[74:75], s[12:13], v74, s1, v[12:13]
	v_mad_i64_i32 v[76:77], s[12:13], v76, s1, v[12:13]
	global_load_dword v93, v[14:15], off nt
	global_load_dword v94, v[16:17], off nt
	global_load_dword v95, v[18:19], off nt
	global_load_dword v96, v[20:21], off nt
	global_load_dword v97, v[22:23], off nt
	global_load_dword v98, v[72:73], off nt
	global_load_dword v99, v[74:75], off nt
	s_nop 0
	global_load_dword v76, v[76:77], off nt
	v_or_b32_e32 v14, 48, v0
	v_or_b32_e32 v16, 50, v0
	v_or_b32_e32 v18, 52, v0
	v_or_b32_e32 v20, 54, v0
	v_or_b32_e32 v22, 56, v0
	v_or_b32_e32 v72, 58, v0
	v_or_b32_e32 v74, 60, v0
	v_or_b32_e32 v0, 62, v0
	v_mad_i64_i32 v[14:15], s[12:13], v14, s1, v[12:13]
	v_mad_i64_i32 v[16:17], s[12:13], v16, s1, v[12:13]
	v_mad_i64_i32 v[18:19], s[12:13], v18, s1, v[12:13]
	v_mad_i64_i32 v[20:21], s[12:13], v20, s1, v[12:13]
	v_mad_i64_i32 v[22:23], s[12:13], v22, s1, v[12:13]
	v_mad_i64_i32 v[72:73], s[12:13], v72, s1, v[12:13]
	v_mad_i64_i32 v[74:75], s[12:13], v74, s1, v[12:13]
	v_mad_i64_i32 v[12:13], s[12:13], v0, s1, v[12:13]
	global_load_dword v0, v[14:15], off nt
	s_nop 0
	global_load_dword v14, v[16:17], off nt
	global_load_dword v15, v[18:19], off nt
	s_nop 0
	global_load_dword v16, v[20:21], off nt
	global_load_dword v17, v[22:23], off nt
	global_load_dword v18, v[72:73], off nt
	global_load_dword v19, v[74:75], off nt
	s_nop 0
	global_load_dword v12, v[12:13], off nt
	s_waitcnt vmcnt(30)
	ds_write2_b32 v62, v71, v78 offset1:66
	s_waitcnt vmcnt(28)
	ds_write2_b32 v62, v79, v80 offset0:132 offset1:198
	s_waitcnt vmcnt(26)
	ds_write2_b32 v64, v81, v82 offset0:8 offset1:74
	s_waitcnt vmcnt(24)
	ds_write2_b32 v64, v83, v84 offset0:140 offset1:206
	s_waitcnt vmcnt(22)
	ds_write2_b32 v65, v85, v86 offset0:16 offset1:82
	s_waitcnt vmcnt(20)
	ds_write2_b32 v65, v87, v88 offset0:148 offset1:214
	s_waitcnt vmcnt(18)
	ds_write2_b32 v66, v89, v90 offset0:24 offset1:90
	s_waitcnt vmcnt(16)
	ds_write2_b32 v66, v91, v92 offset0:156 offset1:222
	s_waitcnt vmcnt(14)
	ds_write2_b32 v67, v93, v94 offset0:32 offset1:98
	s_waitcnt vmcnt(12)
	ds_write2_b32 v67, v95, v96 offset0:164 offset1:230
	s_waitcnt vmcnt(10)
	ds_write2_b32 v68, v97, v98 offset0:40 offset1:106
	s_waitcnt vmcnt(8)
	ds_write2_b32 v68, v99, v76 offset0:172 offset1:238
	s_waitcnt vmcnt(6)
	ds_write2_b32 v69, v0, v14 offset0:48 offset1:114
	s_waitcnt vmcnt(4)
	ds_write2_b32 v69, v15, v16 offset0:180 offset1:246
	s_waitcnt vmcnt(2)
	ds_write2_b32 v70, v17, v18 offset0:56 offset1:122
	s_waitcnt vmcnt(0)
	ds_write2_b32 v70, v19, v12 offset0:188 offset1:254
	s_waitcnt lgkmcnt(0)
	ds_read2_b32 v[14:15], v63 offset1:33
	ds_read2_b32 v[16:17], v63 offset0:66 offset1:99
	ds_read2_b32 v[18:19], v63 offset0:132 offset1:165
	ds_read2_b32 v[20:21], v63 offset0:198 offset1:231
	s_mulk_i32 s6, 0x160
	s_sub_i32 s6, s28, s6
	s_lshl_b32 s6, s6, 5
	v_add_u32_e32 v0, s8, v58
	v_or_b32_e32 v22, s6, v58
	v_cmp_lt_i32_e32 vcc, s27, v0
	s_and_saveexec_b64 s[12:13], vcc
	s_cbranch_execz .LBB0_40
	s_cmpk_lt_u32 s8, 0x2400
	s_mov_b64 s[14:15], -1
	s_cbranch_scc0 .LBB0_38
	v_and_b32_e32 v13, 39, v0
	v_lshlrev_b32_e32 v23, 1, v13
	v_add_u32_e32 v12, 0xfffff000, v0
	v_subrev_u32_e32 v71, 63, v23
	v_cmp_gt_u32_e32 vcc, 32, v13
	s_cmpk_lt_u32 s8, 0x1c00
	v_and_b32_e32 v22, 0xffffffc0, v12
	v_cndmask_b32_e32 v13, v71, v23, vcc
	v_add_u32_e32 v13, v13, v22
	s_cselect_b64 vcc, -1, 0
	v_cndmask_b32_e32 v12, v12, v13, vcc
	v_add_u32_e32 v22, 0x1800, v12
	s_mov_b64 s[14:15], 0

; __device__ __forceinline__ void p0_prologue(const Ptrs& P, LAS unsigned char* lds, int vcu, int G) {
;     ...
;     for (int m = gw; m < TT; m += 2 * NGW) {
;         const int m2 = (m + NGW < TT) ? m + NGW : m;
;         const f32x4* xr = (const f32x4*)(P.x + (size_t)m * DM) + lane; const f32x4* xr2 = (const f32x4*)(P.x + (size_t)m2 * DM) + lane; f32x4 v[4], v2[4]; float s = 0.f, s2 = 0.f;
; #pragma unroll
;         for (int j = 0; j < 4; ++j) { v[j] = xr[64 * j]; v2[j] = xr2[64 * j]; }
; #pragma unroll
;         for (int j = 0; j < 4; ++j) { s += (v[j].x * v[j].x + v[j].y * v[j].y) + (v[j].z * v[j].z + v[j].w * v[j].w); s2 += (v2[j].x * v2[j].x + v2[j].y * v2[j].y) + (v2[j].z * v2[j].z + v2[j].w * v2[j].w); }
;         const float rstd = rsqrtf(wave_sum(s) * (1.0f / DM) + NORM_EPS), rstd2 = rsqrtf(wave_sum(s2) * (1.0f / DM) + NORM_EPS);
.LBB0_57:
	s_add_i32 s8, s0, s17
	s_cmpk_lt_i32 s8, 0x4000
	s_cselect_b32 s10, s8, s0
	s_ashr_i32 s1, s0, 31
	s_lshl_b64 s[12:13], s[0:1], 12
	s_ashr_i32 s11, s10, 31
	v_lshl_add_u64 v[22:23], v[2:3], 0, s[12:13]
	global_load_dwordx4 v[14:17], v[4:5], off nt
	s_lshl_b64 s[12:13], s[10:11], 12
	global_load_dwordx4 v[18:21], v[22:23], off nt
	global_load_dwordx4 v[26:29], v[22:23], off offset:1024 nt
	global_load_dwordx4 v[30:33], v[22:23], off offset:3072 nt
	global_load_dwordx4 v[34:37], v[22:23], off offset:2048 nt
	v_lshl_add_u64 v[22:23], v[2:3], 0, s[12:13]
	global_load_dwordx4 v[38:41], v[22:23], off nt
	global_load_dwordx4 v[42:45], v[22:23], off offset:1024 nt
	global_load_dwordx4 v[46:49], v[22:23], off offset:3072 nt
	global_load_dwordx4 v[50:53], v[22:23], off offset:2048 nt
	s_lshl_b64 s[0:1], s[0:1], 11
	v_lshl_add_u64 v[54:55], v[0:1], 0, s[0:1]
	s_lshl_b64 s[0:1], s[10:11], 11
	v_lshl_add_u64 v[56:57], v[0:1], 0, s[0:1]
	s_waitcnt vmcnt(7)
	v_pk_mul_f32 v[22:23], v[20:21], v[20:21]
	v_pk_mul_f32 v[58:59], v[18:19], v[18:19]
	s_waitcnt vmcnt(6)
	v_pk_mul_f32 v[60:61], v[28:29], v[28:29]
	v_pk_mul_f32 v[62:63], v[26:27], v[26:27]
	s_waitcnt vmcnt(4)
	v_mul_f32_e32 v64, v35, v35
	v_mul_f32_e32 v66, v37, v37
	v_pk_mov_b32 v[68:69], v[58:59], v[22:23] op_sel:[1,0]
	v_mov_b32_e32 v59, v23
	s_waitcnt vmcnt(3)
	v_pk_mul_f32 v[22:23], v[40:41], v[40:41]
	v_pk_mul_f32 v[70:71], v[38:39], v[38:39]
	v_pk_mov_b32 v[72:73], v[62:63], v[60:61] op_sel:[1,0]
	v_mov_b32_e32 v63, v61
	s_waitcnt vmcnt(2)
	v_pk_mul_f32 v[60:61], v[44:45], v[44:45]
	v_pk_mul_f32 v[74:75], v[42:43], v[42:43]
	v_mul_f32_e32 v77, v32, v32
	v_mul_f32_e32 v79, v33, v33
	v_pk_fma_f32 v[64:65], v[34:35], v[34:35], v[64:65] op_sel_hi:[1,1,0]
	v_pk_fma_f32 v[66:67], v[36:37], v[36:37], v[66:67] op_sel_hi:[1,1,0]
	v_pk_add_f32 v[58:59], v[68:69], v[58:59]
	v_pk_mov_b32 v[68:69], v[70:71], v[22:23] op_sel:[1,0]
	v_mov_b32_e32 v71, v23
	v_pk_add_f32 v[22:23], v[72:73], v[62:63]
	v_pk_mov_b32 v[62:63], v[74:75], v[60:61] op_sel:[1,0]
	v_mov_b32_e32 v75, v61
	s_waitcnt vmcnt(0)
	v_mul_f32_e32 v76, v51, v51
	v_mul_f32_e32 v78, v53, v53
	v_mov_b32_e32 v65, v77
	v_mov_b32_e32 v67, v79
	v_pk_add_f32 v[68:69], v[68:69], v[70:71]
	v_pk_add_f32 v[62:63], v[62:63], v[74:75]
	v_mul_f32_e32 v13, v30, v30
	v_mul_f32_e32 v25, v31, v31
	v_mul_f32_e32 v80, v46, v46
	v_mul_f32_e32 v81, v47, v47
	v_mul_f32_e32 v82, v48, v48
	v_mul_f32_e32 v83, v49, v49
	v_pk_fma_f32 v[60:61], v[50:51], v[50:51], v[76:77] op_sel_hi:[1,1,0]
	v_pk_fma_f32 v[72:73], v[52:53], v[52:53], v[78:79] op_sel_hi:[1,1,0]
	v_pk_add_f32 v[58:59], v[58:59], v[58:59] op_sel:[0,1] op_sel_hi:[1,0]
	v_pk_add_f32 v[22:23], v[22:23], v[22:23] op_sel:[0,1] op_sel_hi:[1,0]
	v_pk_add_f32 v[64:65], v[64:65], v[66:67]
	v_pk_add_f32 v[66:67], v[68:69], v[68:69] op_sel:[0,1] op_sel_hi:[1,0]
	v_pk_add_f32 v[62:63], v[62:63], v[62:63] op_sel:[0,1] op_sel_hi:[1,0]
	v_mov_b32_e32 v61, v82
	v_mov_b32_e32 v73, v83
	v_mov_b32_e32 v59, v13
	v_mov_b32_e32 v23, v25
	v_mov_b32_e32 v67, v80
	v_mov_b32_e32 v63, v81
	v_pk_add_f32 v[60:61], v[60:61], v[72:73]
	v_pk_add_f32 v[22:23], v[58:59], v[22:23]
	v_pk_add_f32 v[58:59], v[66:67], v[62:63]
	v_pk_add_f32 v[22:23], v[22:23], v[64:65]
	v_pk_add_f32 v[58:59], v[58:59], v[60:61]
	v_mov_b32_e32 v61, v22
	v_mov_b32_e32 v60, v58
	v_mov_b32_e32 v22, v59
	v_pk_add_f32 v[22:23], v[60:61], v[22:23]
	ds_bpermute_b32 v59, v7, v23
	ds_bpermute_b32 v58, v7, v22
	s_waitcnt lgkmcnt(0)
	v_pk_add_f32 v[22:23], v[22:23], v[58:59]
	ds_bpermute_b32 v59, v8, v23
	ds_bpermute_b32 v58, v8, v22
	s_waitcnt lgkmcnt(0)
	v_pk_add_f32 v[22:23], v[22:23], v[58:59]
	ds_bpermute_b32 v59, v9, v23
	ds_bpermute_b32 v58, v9, v22
	s_waitcnt lgkmcnt(0)
; __device__ __forceinline__ unsigned pk_bf16(float lo, float hi) { typedef __bf16 b2 __attribute__((ext_vector_type(2))); f32x2 v = {lo, hi}; b2 b = __builtin_convertvector(v, b2); return __builtin_bit_cast(unsigned, b); }
; __device__ __forceinline__ void p0_prologue(const Ptrs& P, LAS unsigned char* lds, int vcu, int G) {
;     ...
;         const float rstd = rsqrtf(wave_sum(s) * (1.0f / DM) + NORM_EPS), rstd2 = rsqrtf(wave_sum(s2) * (1.0f / DM) + NORM_EPS);
;         u32x2* o8 = (u32x2*)(H + (size_t)m * DM) + lane; u32x2* o82 = (u32x2*)(H + (size_t)m2 * DM) + lane;
; #pragma unroll
;         for (int j = 0; j < 4; ++j) { const f32x4 w4 = ((const f32x4*)P.norm_w)[lane + 64 * j];
;             o8[64 * j] = (u32x2){pk_bf16(v[j].x * rstd * w4.x, v[j].y * rstd * w4.y), pk_bf16(v[j].z * rstd * w4.z, v[j].w * rstd * w4.w)};
;             o82[64 * j] = (u32x2){pk_bf16(v2[j].x * rstd2 * w4.x, v2[j].y * rstd2 * w4.y), pk_bf16(v2[j].z * rstd2 * w4.z, v2[j].w * rstd2 * w4.w)}; }
	v_pk_add_f32 v[22:23], v[22:23], v[58:59]
	ds_bpermute_b32 v59, v10, v23
	ds_bpermute_b32 v58, v10, v22
	s_waitcnt lgkmcnt(0)
	v_pk_add_f32 v[22:23], v[22:23], v[58:59]
	ds_bpermute_b32 v59, v11, v23
	ds_bpermute_b32 v58, v11, v22
	s_waitcnt lgkmcnt(0)
	v_pk_add_f32 v[22:23], v[22:23], v[58:59]
	ds_bpermute_b32 v59, v12, v23
	ds_bpermute_b32 v58, v12, v22
	s_waitcnt lgkmcnt(0)
	v_pk_add_f32 v[22:23], v[22:23], v[58:59]
	s_nop 0
	v_pk_fma_f32 v[22:23], v[22:23], s[6:7], v[6:7] op_sel_hi:[1,0,0]
	s_nop 0
	v_mul_f32_e32 v13, 0x4b800000, v23
	v_cmp_gt_f32_e64 s[0:1], s7, v23
	v_mul_f32_e32 v25, 0x4b800000, v22
	v_cmp_gt_f32_e32 vcc, s7, v22
	v_cndmask_b32_e64 v13, v23, v13, s[0:1]
	v_rsq_f32_e32 v13, v13
	v_cndmask_b32_e32 v22, v22, v25, vcc
	v_rsq_f32_e32 v23, v22
	v_mul_f32_e32 v22, 0x45800000, v13
	v_cndmask_b32_e64 v22, v13, v22, s[0:1]
	v_mul_f32_e32 v25, 0x45800000, v23
	v_cndmask_b32_e32 v58, v23, v25, vcc
	v_pk_mul_f32 v[18:19], v[18:19], v[22:23] op_sel_hi:[1,0]
	v_pk_mul_f32 v[20:21], v[20:21], v[22:23] op_sel_hi:[1,0]
	v_pk_mul_f32 v[38:39], v[38:39], v[58:59] op_sel_hi:[1,0]
	v_pk_mul_f32 v[40:41], v[40:41], v[58:59] op_sel_hi:[1,0]
	v_pk_mul_f32 v[18:19], v[14:15], v[18:19]
	v_pk_mul_f32 v[20:21], v[16:17], v[20:21]
	v_pk_mul_f32 v[14:15], v[14:15], v[38:39]
	v_pk_mul_f32 v[16:17], v[16:17], v[40:41]
	v_cvt_pk_bf16_f32 v18, v18, v19
	v_cvt_pk_bf16_f32 v19, v20, v21
	v_cvt_pk_bf16_f32 v14, v14, v15
	v_cvt_pk_bf16_f32 v15, v16, v17
	global_store_dwordx2 v[54:55], v[18:19], off
	global_store_dwordx2 v[56:57], v[14:15], off
	global_load_dwordx4 v[14:17], v[4:5], off offset:1024 nt
	v_pk_mul_f32 v[18:19], v[26:27], v[22:23] op_sel_hi:[1,0]
	v_pk_mul_f32 v[20:21], v[28:29], v[22:23] op_sel_hi:[1,0]
	v_pk_mul_f32 v[26:27], v[42:43], v[58:59] op_sel_hi:[1,0]
	v_pk_mul_f32 v[28:29], v[44:45], v[58:59] op_sel_hi:[1,0]
	s_add_i32 s0, s8, s17
	s_cmpk_gt_i32 s0, 0x3fff
	s_waitcnt vmcnt(0)
	v_pk_mul_f32 v[18:19], v[14:15], v[18:19]
	v_pk_mul_f32 v[20:21], v[16:17], v[20:21]
	v_pk_mul_f32 v[14:15], v[14:15], v[26:27]
	v_pk_mul_f32 v[16:17], v[16:17], v[28:29]
	v_cvt_pk_bf16_f32 v18, v18, v19
	v_cvt_pk_bf16_f32 v19, v20, v21
	v_cvt_pk_bf16_f32 v14, v14, v15
	v_cvt_pk_bf16_f32 v15, v16, v17
	global_store_dwordx2 v[54:55], v[18:19], off offset:512
	global_store_dwordx2 v[56:57], v[14:15], off offset:512
	global_load_dwordx4 v[14:17], v[4:5], off offset:2048 nt
	v_pk_mul_f32 v[18:19], v[34:35], v[22:23] op_sel_hi:[1,0]
	v_pk_mul_f32 v[20:21], v[36:37], v[22:23] op_sel_hi:[1,0]
	v_pk_mul_f32 v[26:27], v[50:51], v[58:59] op_sel_hi:[1,0]
	v_pk_mul_f32 v[28:29], v[52:53], v[58:59] op_sel_hi:[1,0]
	s_waitcnt vmcnt(0)
	v_pk_mul_f32 v[18:19], v[18:19], v[14:15]
	v_pk_mul_f32 v[20:21], v[20:21], v[16:17]
	v_pk_mul_f32 v[14:15], v[14:15], v[26:27]
	v_pk_mul_f32 v[16:17], v[16:17], v[28:29]
	v_cvt_pk_bf16_f32 v18, v18, v19
	v_cvt_pk_bf16_f32 v19, v20, v21
	v_cvt_pk_bf16_f32 v14, v14, v15
	v_cvt_pk_bf16_f32 v15, v16, v17
	global_store_dwordx2 v[54:55], v[18:19], off offset:1024
	global_store_dwordx2 v[56:57], v[14:15], off offset:1024
	global_load_dwordx4 v[14:17], v[4:5], off offset:3072 nt
	v_pk_mul_f32 v[18:19], v[30:31], v[22:23] op_sel_hi:[1,0]
	v_pk_mul_f32 v[20:21], v[32:33], v[22:23] op_sel_hi:[1,0]
	v_pk_mul_f32 v[22:23], v[46:47], v[58:59] op_sel_hi:[1,0]
	v_pk_mul_f32 v[26:27], v[48:49], v[58:59] op_sel_hi:[1,0]
	s_waitcnt vmcnt(0)
	v_pk_mul_f32 v[18:19], v[18:19], v[14:15]
	v_pk_mul_f32 v[20:21], v[20:21], v[16:17]
	v_pk_mul_f32 v[14:15], v[22:23], v[14:15]
	v_pk_mul_f32 v[16:17], v[26:27], v[16:17]
	v_cvt_pk_bf16_f32 v18, v18, v19
	v_cvt_pk_bf16_f32 v19, v20, v21
	v_cvt_pk_bf16_f32 v14, v14, v15
	v_cvt_pk_bf16_f32 v15, v16, v17
	global_store_dwordx2 v[54:55], v[18:19], off offset:1536
	global_store_dwordx2 v[56:57], v[14:15], off offset:1536
	s_cbranch_scc0 .LBB0_57

; __device__ __forceinline__ void p0_prologue(const Ptrs& P, LAS unsigned char* lds, int vcu, int G) {
;     ...
;     float* cosT = (float*)(P.ws + WS_COS); float* sinT = (float*)(P.ws + WS_SIN);
;     for (int e = (vcu * 512 + tid); e < TT * 32; e += G * 512) {
;         const int row = e >> 5, j = e & 31;
;         const float inv = exp2f(-(float)j * (13.287712379549449f / 32.0f));
;         const float ang = (float)P.pos[row] * inv;
;         const double rev = (double)ang * 0.15915494309189535; const float fr = (float)(rev - __builtin_rint(rev));
;         cosT[e] = __builtin_amdgcn_cosf(fr); sinT[e] = __builtin_amdgcn_sinf(fr);
;     }
.LBB0_60:
	v_ashrrev_i32_e32 v6, 5, v0
	v_ashrrev_i32_e32 v7, 31, v6
	s_waitcnt lgkmcnt(0)
	v_lshl_add_u64 v[6:7], v[6:7], 2, s[58:59]
	global_load_dword v1, v[6:7], off nt
	v_add_co_u32_e32 v6, vcc, 0x200000, v2
	v_add_u32_e32 v0, s6, v0
	s_nop 0
	v_addc_co_u32_e32 v7, vcc, 0, v3, vcc
	v_cmp_lt_i32_e32 vcc, s7, v0
	s_or_b64 s[10:11], vcc, s[10:11]
	s_waitcnt vmcnt(0)
	v_cvt_f32_i32_e32 v1, v1
	v_mul_f32_e32 v1, v4, v1
	v_cvt_f64_f32_e32 v[8:9], v1
	v_mul_f64 v[10:11], v[8:9], s[12:13]
	v_rndne_f64_e32 v[10:11], v[10:11]
	v_fma_f64 v[8:9], v[8:9], s[12:13], -v[10:11]
	v_cvt_f32_f64_e32 v1, v[8:9]
	v_cos_f32_e32 v5, v1
	v_sin_f32_e32 v1, v1
	global_store_dword v[2:3], v5, off
	global_store_dword v[6:7], v1, off
	v_lshl_add_u64 v[2:3], v[2:3], 0, s[8:9]
	s_andn2_b64 exec, exec, s[10:11]
	s_cbranch_execnz .LBB0_60
